# ring-4 variant without the static priority raise for waves 4-7
# speedup vs baseline: 1.0013x; 1.0013x over previous
; DI void attn_phase(LAS unsigned char* lds, const int wid, const bf16_t* Q, const bf16_t* Kn, const bf16_t* Kr, const bf16_t* Vt, bf16_t* O, int G, int c) {
;     ...
;         u32x4 akn = *(const u32x4*)(gkn + (size_t)2 * 64 * 512), avt = *(const u32x4*)(gvt + 64), akr = {0u, 0u, 0u, 0u}, bkn, bkr = {0u, 0u, 0u, 0u}, bvt;
;         if (tid < 256) akr = *(const u32x4*)(gkr + (size_t)2 * 64 * 32);
;         if (wid >= 4) __builtin_amdgcn_s_setprio(1);
.LBB0_870:
	s_or_b64 exec, exec, s[48:49]
	s_andn2_b64 vcc, exec, s[38:39]
	s_cbranch_vccnz .LBB0_872
	s_setprio 0
